# NSA unit start: second compressed K/V load pair hoisted before the first wait; selected-branch tiles 0/1 prefetched at unit start into spare registers
# speedup vs baseline: 1.0026x; 1.0026x over previous
.LBB0_939:
	s_cbranch_execz .LBB0_870
	s_lshl_b32 s1, s0, 2
	s_ashr_i32 s2, s0, 1
	s_and_b32 s1, s1, 4
	v_readlane_b32 s3, v240, 42
	s_add_i32 s12, s1, s3
	s_lshl_b32 s1, s2, 3
	s_add_i32 s4, s12, s1
	s_ashr_i32 s5, s4, 31
	v_lshl_or_b32 v64, s93, 6, v193
	s_ashr_i32 s3, s2, 31
	s_lshl_b64 s[4:5], s[4:5], 18
	v_readlane_b32 s1, v240, 38
	v_ashrrev_i32_e32 v65, 31, v64
	s_add_u32 s4, s1, s4
	v_readlane_b32 s1, v240, 39
	s_addc_u32 s5, s1, s5
	v_lshlrev_b64 v[0:1], 7, v[64:65]
	v_lshl_add_u64 v[0:1], s[4:5], 0, v[0:1]
	s_lshl_b64 s[2:3], s[2:3], 11
	v_lshl_add_u64 v[0:1], v[0:1], 0, v[150:151]
	v_lshl_add_u64 v[146:147], s[2:3], 0, v[64:65]
	v_readlane_b32 s2, v240, 40
	global_load_dwordx4 v[80:83], v[0:1], off
	global_load_dwordx4 v[84:87], v[0:1], off offset:32
	global_load_dwordx4 v[88:91], v[0:1], off offset:64
	global_load_dwordx4 v[92:95], v[0:1], off offset:96
	v_lshlrev_b64 v[0:1], 7, v[146:147]
	v_readlane_b32 s3, v240, 41
	v_writelane_b32 v240, s12, 18
	s_ashr_i32 s1, s0, 31
	v_lshl_add_u64 v[0:1], s[2:3], 0, v[0:1]
	s_lshl_b64 s[2:3], s[0:1], 14
	v_readlane_b32 s4, v240, 30
	v_readlane_b32 s5, v240, 31
	s_add_u32 s4, s4, s2
	s_mul_i32 s96, s12, 12
	s_addc_u32 s5, s5, s3
	v_readlane_b32 s12, v240, 32
	v_readlane_b32 s13, v240, 33
	s_add_u32 s2, s12, s2
	s_addc_u32 s3, s13, s3
	v_lshl_add_u64 v[0:1], v[0:1], 0, s[96:97]
	v_lshl_add_u64 v[4:5], s[2:3], 0, v[152:153]
	global_load_dwordx3 v[128:130], v[0:1], off
	v_add_u32_e32 v131, v159, v132
	global_load_dwordx4 v[4:7], v[4:5], off
	v_lshl_add_u64 v[0:1], s[4:5], 0, v[152:153]
	global_load_dwordx4 v[0:3], v[0:1], off
	v_lshl_add_u64 v[8:9], s[4:5], 0, v[140:141]
	global_load_dwordx4 v[8:11], v[8:9], off
	v_lshl_add_u64 v[12:13], s[2:3], 0, v[140:141]
	global_load_dwordx4 v[12:15], v[12:13], off
	s_mov_b32 s98, s0
	s_ashr_i32 s99, s0, 31
	s_lshl_b64 s[98:99], s[98:99], 18
	v_readlane_b32 s100, v240, 49
	v_readlane_b32 s101, v240, 50
	s_add_u32 s100, s100, s98
	s_addc_u32 s101, s101, s99
	v_lshl_add_u64 v[236:237], s[100:101], 0, v[152:153]
	global_load_dwordx4 v[220:223], v[236:237], off
	v_readlane_b32 s100, v240, 47
	v_readlane_b32 s101, v240, 48
	s_add_u32 s100, s100, s98
	s_addc_u32 s101, s101, s99
	v_lshl_add_u64 v[238:239], s[100:101], 0, v[152:153]
	global_load_dwordx4 v[216:219], v[238:239], off
	s_mov_b64 s[100:101], 0x2000
	v_lshl_add_u64 v[238:239], v[238:239], 0, s[100:101]
	v_lshl_add_u64 v[236:237], v[236:237], 0, s[100:101]
	global_load_dwordx4 v[224:227], v[238:239], off
	global_load_dwordx4 v[228:231], v[236:237], off
	v_cmp_lt_i32_e32 vcc, 30, v64
	s_waitcnt vmcnt(0)
	ds_write_b128 v206, v[0:3]
	ds_write_b128 v207, v[4:7] offset:18432
	s_movk_i32 s2, 0x41
	s_mov_b64 s[4:5], -1
	ds_write_b128 v208, v[8:11]
	ds_write_b128 v209, v[12:15] offset:18432
	v_subrev_u32_e32 v0, 31, v64
	s_waitcnt lgkmcnt(0)
	s_barrier
	v_lshrrev_b32_e32 v65, 4, v0
	ds_read_b128 v[0:3], v131
	ds_read_b128 v[4:7], v131 offset:32
	s_waitcnt lgkmcnt(1)
	v_mfma_f32_32x32x16_bf16 v[48:63], v[0:3], v[80:83], 0
	ds_read_b128 v[0:3], v131 offset:64
	ds_read_b128 v[66:69], v131 offset:13856
	v_cndmask_b32_e32 v64, -1, v65, vcc
	v_sub_u32_e32 v64, v64, v138
	v_cmp_gt_i32_e64 s[40:41], 26, v64
	v_cmp_gt_i32_e64 s[42:43], 27, v64
	v_cmp_gt_i32_e64 s[38:39], 25, v64
	s_waitcnt lgkmcnt(2)
	v_mfma_f32_32x32x16_bf16 v[48:63], v[4:7], v[84:87], v[48:63]
	v_cmp_gt_i32_e64 s[36:37], 24, v64
	v_cmp_gt_i32_e64 s[34:35], 19, v64
	v_cmp_gt_i32_e64 s[30:31], 18, v64
	v_cmp_lt_i32_e32 vcc, -1, v64
	v_cmp_gt_i32_e64 s[28:29], 17, v64
	v_cmp_gt_i32_e64 s[26:27], 16, v64
	v_cmp_gt_i32_e64 s[14:15], 2, v64
	s_waitcnt lgkmcnt(1)
	v_mfma_f32_32x32x16_bf16 v[48:63], v[0:3], v[88:91], v[48:63]
	ds_read_b128 v[0:3], v131 offset:96
	v_cmp_gt_i32_e64 s[16:17], 3, v64
	v_cmp_gt_i32_e64 s[24:25], 11, v64
	v_cmp_gt_i32_e64 s[18:19], 8, v64
	v_cmp_gt_i32_e64 s[20:21], 9, v64
	v_cmp_gt_i32_e64 s[22:23], 10, v64
	s_waitcnt lgkmcnt(0)
	v_mfma_f32_32x32x16_bf16 v[48:63], v[0:3], v[92:95], v[48:63]
	ds_read_b128 v[0:3], v131 offset:4608
	s_waitcnt lgkmcnt(0)
	v_mfma_f32_32x32x16_bf16 v[32:47], v[0:3], v[80:83], 0
	ds_read_b128 v[0:3], v131 offset:4640
	s_nop 7
	v_cndmask_b32_e64 v96, v62, v210, s[40:41]
	s_and_b64 s[40:41], s[42:43], s[40:41]
	v_cndmask_b32_e64 v79, v61, v210, s[38:39]
	s_and_b64 s[38:39], s[40:41], s[38:39]
	v_cndmask_b32_e64 v78, v60, v210, s[36:37]
	s_and_b64 s[36:37], s[38:39], s[36:37]
	s_waitcnt lgkmcnt(0)
	v_mfma_f32_32x32x16_bf16 v[32:47], v[0:3], v[84:87], v[32:47]
	ds_read_b128 v[0:3], v131 offset:4672
	v_cndmask_b32_e64 v77, v59, v210, s[34:35]
	s_and_b64 s[34:35], s[36:37], s[34:35]
	v_cndmask_b32_e64 v76, v58, v210, s[30:31]
	s_and_b64 s[30:31], s[34:35], s[30:31]
	v_cndmask_b32_e32 v65, v210, v48, vcc
	v_cmp_gt_i32_e32 vcc, 1, v64
	s_waitcnt lgkmcnt(0)
	v_mfma_f32_32x32x16_bf16 v[32:47], v[0:3], v[88:91], v[32:47]
	ds_read_b128 v[0:3], v131 offset:4704
	v_cndmask_b32_e64 v75, v57, v210, s[28:29]
	s_and_b64 s[28:29], s[30:31], s[28:29]
	v_cndmask_b32_e64 v74, v56, v210, s[26:27]
	s_and_b64 s[26:27], s[28:29], s[26:27]
	v_cndmask_b32_e64 v73, v55, v210, s[24:25]
	s_and_b64 s[24:25], s[26:27], s[24:25]
	s_waitcnt lgkmcnt(0)
	v_mfma_f32_32x32x16_bf16 v[32:47], v[0:3], v[92:95], v[32:47]
	ds_read_b128 v[0:3], v131 offset:9216
	v_cndmask_b32_e64 v70, v52, v210, s[18:19]
	v_cndmask_b32_e64 v71, v53, v210, s[20:21]
	v_cndmask_b32_e64 v72, v54, v210, s[22:23]
	s_and_b64 s[22:23], s[24:25], s[22:23]
	s_and_b64 s[20:21], s[22:23], s[20:21]
	s_and_b64 s[18:19], s[20:21], s[18:19]
	s_waitcnt lgkmcnt(0)
	v_mfma_f32_32x32x16_bf16 v[16:31], v[0:3], v[80:83], 0
	ds_read_b128 v[0:3], v131 offset:9248
	v_cndmask_b32_e64 v62, v62, v96, s[42:43]
	v_cndmask_b32_e64 v61, v61, v79, s[40:41]
	v_cndmask_b32_e64 v63, v63, v210, s[42:43]
	v_cmp_gt_i32_e64 s[40:41], 58, v64
	v_cmp_gt_i32_e64 s[42:43], 59, v64
	v_cndmask_b32_e64 v60, v60, v78, s[38:39]
	s_waitcnt lgkmcnt(0)
	v_mfma_f32_32x32x16_bf16 v[16:31], v[0:3], v[84:87], v[16:31]
	ds_read_b128 v[0:3], v131 offset:9280
	v_cmp_gt_i32_e64 s[38:39], 57, v64
	v_cndmask_b32_e64 v59, v59, v77, s[36:37]
	v_cmp_gt_i32_e64 s[36:37], 56, v64
	v_cndmask_b32_e64 v58, v58, v76, s[34:35]
	v_cmp_gt_i32_e64 s[34:35], 51, v64
	s_waitcnt lgkmcnt(0)
	v_mfma_f32_32x32x16_bf16 v[16:31], v[0:3], v[88:91], v[16:31]
	ds_read_b128 v[0:3], v131 offset:9312
	s_waitcnt lgkmcnt(0)
	v_mfma_f32_32x32x16_bf16 v[16:31], v[0:3], v[92:95], v[16:31]
	ds_read_b128 v[0:3], v131 offset:13824
	s_waitcnt lgkmcnt(0)
	v_mfma_f32_32x32x16_bf16 v[0:15], v[0:3], v[80:83], 0
	v_mfma_f32_32x32x16_bf16 v[0:15], v[66:69], v[84:87], v[0:15]
	ds_read_b128 v[66:69], v131 offset:13888
	s_waitcnt lgkmcnt(0)
	v_mfma_f32_32x32x16_bf16 v[0:15], v[66:69], v[88:91], v[0:15]
	ds_read_b128 v[66:69], v131 offset:13920
	s_waitcnt lgkmcnt(0)
	v_mfma_f32_32x32x16_bf16 v[0:15], v[66:69], v[92:95], v[0:15]
	v_cndmask_b32_e32 v66, v49, v210, vcc
	v_max3_f32 v67, v65, s33, v66
	v_cndmask_b32_e64 v68, v50, v210, s[14:15]
	v_cndmask_b32_e64 v69, v51, v210, s[16:17]
	v_max3_f32 v67, v67, v68, v69
	v_max3_f32 v67, v67, v70, v71
	v_max3_f32 v67, v67, v72, v73
	v_max3_f32 v67, v67, v74, v75
	s_and_b64 s[16:17], s[18:19], s[16:17]
	v_max3_f32 v67, v67, v76, v77
	s_and_b64 s[14:15], s[16:17], s[14:15]
	v_max3_f32 v67, v67, v78, v79
	s_and_b64 vcc, s[14:15], vcc
	v_cndmask_b32_e32 v65, v48, v65, vcc
	v_max3_f32 v48, v67, v96, v63
	v_cndmask_b32_e64 v96, v46, v210, s[40:41]
	s_and_b64 s[40:41], s[42:43], s[40:41]
	v_cndmask_b32_e64 v79, v45, v210, s[38:39]
	s_and_b64 s[38:39], s[40:41], s[38:39]
	v_cndmask_b32_e64 v78, v44, v210, s[36:37]
	s_and_b64 s[36:37], s[38:39], s[36:37]
	v_cndmask_b32_e64 v75, v57, v75, s[30:31]
	v_cmp_gt_i32_e64 s[30:31], 50, v64
	v_cndmask_b32_e64 v77, v43, v210, s[34:35]
	s_and_b64 s[34:35], s[36:37], s[34:35]
	v_cndmask_b32_e64 v74, v56, v74, s[28:29]
	v_cmp_gt_i32_e64 s[28:29], 49, v64
	v_cndmask_b32_e64 v76, v42, v210, s[30:31]
	s_and_b64 s[30:31], s[34:35], s[30:31]
	v_cndmask_b32_e64 v73, v55, v73, s[26:27]
	v_cmp_gt_i32_e64 s[26:27], 48, v64
	v_cndmask_b32_e64 v67, v41, v210, s[28:29]
	s_and_b64 s[28:29], s[30:31], s[28:29]
	v_cndmask_b32_e64 v72, v54, v72, s[24:25]
	v_cmp_lt_i32_e32 vcc, 31, v64
	v_cmp_gt_i32_e64 s[24:25], 43, v64
	v_cndmask_b32_e64 v57, v40, v210, s[26:27]
	s_and_b64 s[26:27], s[28:29], s[26:27]
	v_cndmask_b32_e64 v71, v53, v71, s[22:23]
	v_cndmask_b32_e64 v66, v49, v66, s[14:15]
	v_cndmask_b32_e32 v49, v210, v32, vcc
	v_cmp_gt_i32_e32 vcc, 33, v64
	v_cmp_gt_i32_e64 s[22:23], 42, v64
	v_cndmask_b32_e64 v56, v39, v210, s[24:25]
	s_and_b64 s[24:25], s[26:27], s[24:25]
	v_cndmask_b32_e64 v70, v52, v70, s[20:21]
	v_cndmask_b32_e64 v68, v50, v68, s[16:17]
	v_cndmask_b32_e32 v50, v33, v210, vcc
	v_cmp_gt_i32_e64 s[14:15], 34, v64
	v_cmp_gt_i32_e64 s[16:17], 35, v64
	v_cmp_gt_i32_e64 s[20:21], 41, v64
	v_cndmask_b32_e64 v55, v38, v210, s[22:23]
	s_and_b64 s[22:23], s[24:25], s[22:23]
	v_cndmask_b32_e64 v69, v51, v69, s[18:19]
	v_max3_f32 v48, v48, v49, v50
	v_cndmask_b32_e64 v51, v34, v210, s[14:15]
	v_cndmask_b32_e64 v52, v35, v210, s[16:17]
	v_cmp_gt_i32_e64 s[18:19], 40, v64
	v_cndmask_b32_e64 v54, v37, v210, s[20:21]
	s_and_b64 s[20:21], s[22:23], s[20:21]
	v_max3_f32 v48, v48, v51, v52
	v_cndmask_b32_e64 v53, v36, v210, s[18:19]
	s_and_b64 s[18:19], s[20:21], s[18:19]
	v_max3_f32 v48, v48, v53, v54
	s_and_b64 s[16:17], s[18:19], s[16:17]
	v_max3_f32 v48, v48, v55, v56
	s_and_b64 s[14:15], s[16:17], s[14:15]
	v_max3_f32 v48, v48, v57, v67
	s_and_b64 vcc, s[14:15], vcc
	v_max3_f32 v48, v48, v76, v77
	v_cndmask_b32_e32 v32, v32, v49, vcc
	v_cmp_lt_i32_e32 vcc, 63, v64
	v_max3_f32 v48, v48, v78, v79
	v_cndmask_b32_e64 v79, v45, v79, s[40:41]
	v_cndmask_b32_e32 v45, v210, v16, vcc
	v_cmp_gt_i32_e32 vcc, s2, v64
	s_movk_i32 s2, 0x42
	v_cndmask_b32_e64 v33, v33, v50, s[14:15]
	v_cmp_gt_i32_e64 s[14:15], s2, v64
	s_movk_i32 s2, 0x43
	v_cndmask_b32_e64 v34, v34, v51, s[16:17]
	v_cmp_gt_i32_e64 s[16:17], s2, v64
	s_movk_i32 s2, 0x48
	v_cndmask_b32_e64 v35, v35, v52, s[18:19]
	v_cmp_gt_i32_e64 s[18:19], s2, v64
	s_movk_i32 s2, 0x49
	v_cndmask_b32_e64 v36, v36, v53, s[20:21]
	v_cmp_gt_i32_e64 s[20:21], s2, v64
	s_movk_i32 s2, 0x4a
	v_cndmask_b32_e64 v37, v37, v54, s[22:23]
	v_cmp_gt_i32_e64 s[22:23], s2, v64
	s_movk_i32 s2, 0x4b
	v_cndmask_b32_e64 v38, v38, v55, s[24:25]
	v_cmp_gt_i32_e64 s[24:25], s2, v64
	s_movk_i32 s2, 0x50
	v_cndmask_b32_e64 v39, v39, v56, s[26:27]
	v_cmp_gt_i32_e64 s[26:27], s2, v64
	s_movk_i32 s2, 0x51
	v_cndmask_b32_e64 v40, v40, v57, s[28:29]
	v_cmp_gt_i32_e64 s[28:29], s2, v64
	s_movk_i32 s2, 0x52
	v_cndmask_b32_e64 v41, v41, v67, s[30:31]
	v_cmp_gt_i32_e64 s[30:31], s2, v64
	s_movk_i32 s2, 0x53
	v_cndmask_b32_e64 v42, v42, v76, s[34:35]
	v_cmp_gt_i32_e64 s[34:35], s2, v64
	s_movk_i32 s2, 0x58
	v_cndmask_b32_e64 v43, v43, v77, s[36:37]
	v_cmp_gt_i32_e64 s[36:37], s2, v64
	s_movk_i32 s2, 0x59
	v_cndmask_b32_e64 v78, v44, v78, s[38:39]
	v_cmp_gt_i32_e64 s[38:39], s2, v64
	s_movk_i32 s2, 0x5a
	v_cmp_gt_i32_e64 s[40:41], s2, v64
	s_movk_i32 s2, 0x5b
	v_cndmask_b32_e64 v97, v46, v96, s[42:43]
	v_cndmask_b32_e64 v67, v47, v210, s[42:43]
	v_cmp_gt_i32_e64 s[42:43], s2, v64
	v_max3_f32 v44, v48, v96, v67
	v_cndmask_b32_e64 v96, v30, v210, s[40:41]
	s_and_b64 s[40:41], s[42:43], s[40:41]
	v_cndmask_b32_e64 v54, v29, v210, s[38:39]
	s_and_b64 s[38:39], s[40:41], s[38:39]
	v_cndmask_b32_e64 v55, v28, v210, s[36:37]
	s_and_b64 s[36:37], s[38:39], s[36:37]
	v_cndmask_b32_e64 v77, v27, v210, s[34:35]
	s_and_b64 s[34:35], s[36:37], s[34:35]
	v_cndmask_b32_e64 v76, v26, v210, s[30:31]
	s_and_b64 s[30:31], s[34:35], s[30:31]
	v_cndmask_b32_e64 v57, v25, v210, s[28:29]
	s_and_b64 s[28:29], s[30:31], s[28:29]
	v_cndmask_b32_e64 v56, v24, v210, s[26:27]
	s_and_b64 s[26:27], s[28:29], s[26:27]
	v_cndmask_b32_e64 v53, v23, v210, s[24:25]
	s_and_b64 s[24:25], s[26:27], s[24:25]
	v_cndmask_b32_e64 v51, v22, v210, s[22:23]
	s_and_b64 s[22:23], s[24:25], s[22:23]
	v_cndmask_b32_e64 v50, v21, v210, s[20:21]
	s_and_b64 s[20:21], s[22:23], s[20:21]
	v_cndmask_b32_e64 v49, v20, v210, s[18:19]
	s_and_b64 s[18:19], s[20:21], s[18:19]
	v_cndmask_b32_e64 v48, v19, v210, s[16:17]
	s_and_b64 s[16:17], s[18:19], s[16:17]
	v_cndmask_b32_e64 v47, v18, v210, s[14:15]
	s_and_b64 s[14:15], s[16:17], s[14:15]
	v_cndmask_b32_e32 v46, v17, v210, vcc
	s_and_b64 vcc, s[14:15], vcc
	s_movk_i32 s2, 0x5f
	v_cndmask_b32_e32 v107, v16, v45, vcc
	v_cmp_lt_i32_e32 vcc, s2, v64
	s_movk_i32 s2, 0x61
	v_cndmask_b32_e64 v106, v17, v46, s[14:15]
	v_cndmask_b32_e32 v17, v210, v0, vcc
	v_cmp_gt_i32_e32 vcc, s2, v64
	s_movk_i32 s2, 0x62
	v_cmp_gt_i32_e64 s[14:15], s2, v64
	s_movk_i32 s2, 0x63
	v_cndmask_b32_e64 v105, v18, v47, s[16:17]
	v_cmp_gt_i32_e64 s[16:17], s2, v64
	s_movk_i32 s2, 0x68
	v_cndmask_b32_e64 v104, v19, v48, s[18:19]
	v_cmp_gt_i32_e64 s[18:19], s2, v64
	s_movk_i32 s2, 0x69
	v_cndmask_b32_e64 v103, v20, v49, s[20:21]
	v_cmp_gt_i32_e64 s[20:21], s2, v64
	s_movk_i32 s2, 0x6a
	v_max3_f32 v44, v44, v45, v46
	v_cndmask_b32_e64 v102, v21, v50, s[22:23]
	v_cmp_gt_i32_e64 s[22:23], s2, v64
	s_movk_i32 s2, 0x6b
	v_max3_f32 v44, v44, v47, v48
	v_cndmask_b32_e64 v101, v22, v51, s[24:25]
	v_cmp_gt_i32_e64 s[24:25], s2, v64
	s_movk_i32 s2, 0x70
	v_max3_f32 v44, v44, v49, v50
	v_cndmask_b32_e64 v100, v23, v53, s[26:27]
	v_cmp_gt_i32_e64 s[26:27], s2, v64
	s_movk_i32 s2, 0x71
	v_max3_f32 v44, v44, v51, v53
	v_cndmask_b32_e64 v99, v24, v56, s[28:29]
	v_cmp_gt_i32_e64 s[28:29], s2, v64
	s_movk_i32 s2, 0x72
	v_max3_f32 v44, v44, v56, v57
	v_cndmask_b32_e64 v98, v25, v57, s[30:31]
	v_cmp_gt_i32_e64 s[30:31], s2, v64
	s_movk_i32 s2, 0x73
	v_max3_f32 v44, v44, v76, v77
	v_cndmask_b32_e64 v76, v26, v76, s[34:35]
	v_cmp_gt_i32_e64 s[34:35], s2, v64
	s_movk_i32 s2, 0x78
	v_cndmask_b32_e64 v77, v27, v77, s[36:37]
	v_cmp_gt_i32_e64 s[36:37], s2, v64
	s_movk_i32 s2, 0x79
	v_max3_f32 v44, v44, v55, v54
	v_cndmask_b32_e64 v55, v28, v55, s[38:39]
	v_cmp_gt_i32_e64 s[38:39], s2, v64
	s_movk_i32 s2, 0x7a
	v_cndmask_b32_e64 v54, v29, v54, s[40:41]
	v_cmp_gt_i32_e64 s[40:41], s2, v64
	s_movk_i32 s2, 0x7b
	v_cndmask_b32_e64 v52, v30, v96, s[42:43]
	v_cndmask_b32_e64 v57, v31, v210, s[42:43]
	v_cmp_gt_i32_e64 s[42:43], s2, v64
	v_cndmask_b32_e64 v31, v14, v210, s[40:41]
	s_and_b64 s[40:41], s[42:43], s[40:41]
	v_cndmask_b32_e64 v30, v13, v210, s[38:39]
	s_and_b64 s[38:39], s[40:41], s[38:39]
	v_cndmask_b32_e64 v29, v12, v210, s[36:37]
	s_and_b64 s[36:37], s[38:39], s[36:37]
	v_cndmask_b32_e64 v28, v11, v210, s[34:35]
	s_and_b64 s[34:35], s[36:37], s[34:35]
	v_cndmask_b32_e64 v27, v10, v210, s[30:31]
	s_and_b64 s[30:31], s[34:35], s[30:31]
	v_cndmask_b32_e64 v26, v9, v210, s[28:29]
	s_and_b64 s[28:29], s[30:31], s[28:29]
	v_max3_f32 v16, v44, v96, v57
	v_cndmask_b32_e32 v18, v1, v210, vcc
	v_cndmask_b32_e64 v25, v8, v210, s[26:27]
	s_and_b64 s[26:27], s[28:29], s[26:27]
	v_max3_f32 v16, v16, v17, v18
	v_cndmask_b32_e64 v19, v2, v210, s[14:15]
	v_cndmask_b32_e64 v20, v3, v210, s[16:17]
	v_cndmask_b32_e64 v24, v7, v210, s[24:25]
	s_and_b64 s[24:25], s[26:27], s[24:25]
	v_max3_f32 v16, v16, v19, v20
	v_cndmask_b32_e64 v21, v4, v210, s[18:19]
	v_cndmask_b32_e64 v22, v5, v210, s[20:21]
	v_cndmask_b32_e64 v23, v6, v210, s[22:23]
	s_and_b64 s[22:23], s[24:25], s[22:23]
	v_max3_f32 v16, v16, v21, v22
	s_and_b64 s[20:21], s[22:23], s[20:21]
	v_max3_f32 v16, v16, v23, v24
	s_and_b64 s[18:19], s[20:21], s[18:19]
	v_max3_f32 v16, v16, v25, v26
	s_and_b64 s[16:17], s[18:19], s[16:17]
	v_max3_f32 v16, v16, v27, v28
	s_and_b64 s[14:15], s[16:17], s[14:15]
	v_max3_f32 v16, v16, v29, v30
	s_and_b64 vcc, s[14:15], vcc
	v_cndmask_b32_e64 v47, v15, v210, s[42:43]
	v_cndmask_b32_e32 v96, v0, v17, vcc
	v_max3_f32 v0, v16, v31, v47
	v_cndmask_b32_e64 v111, v2, v19, s[16:17]
	v_cndmask_b32_e64 v112, v1, v18, s[14:15]
	v_mov_b32_e32 v1, v0
	v_mov_b32_e32 v2, v0
	s_nop 1
	v_permlane32_swap_b32_e32 v1, v2
	v_cndmask_b32_e64 v1, v1, v2, s[6:7]
	v_max_f32_e32 v1, v1, v1
	v_max_f32_e32 v0, v0, v1
	v_cmp_neq_f32_e32 vcc, s33, v0
	v_cndmask_b32_e64 v110, v3, v20, s[18:19]
	v_cndmask_b32_e64 v109, v4, v21, s[20:21]
	v_cndmask_b32_e32 v48, 0, v0, vcc
	v_sub_f32_e32 v0, v65, v48
	v_exp_f32_e32 v0, v0
	v_sub_f32_e32 v1, v66, v48
	v_exp_f32_e32 v1, v1
	v_cndmask_b32_e64 v108, v5, v22, s[22:23]
	v_add_f32_e32 v2, 0, v0
	v_cndmask_b32_e64 v64, v6, v23, s[24:25]
	v_add_f32_e32 v3, v1, v2
	v_sub_f32_e32 v2, v68, v48
	v_exp_f32_e32 v2, v2
	v_cndmask_b32_e64 v56, v7, v24, s[26:27]
	v_cndmask_b32_e64 v53, v8, v25, s[28:29]
	v_cndmask_b32_e64 v51, v9, v26, s[30:31]
	v_add_f32_e32 v4, v2, v3
	v_sub_f32_e32 v3, v69, v48
	v_exp_f32_e32 v3, v3
	v_cndmask_b32_e64 v50, v10, v27, s[34:35]
	v_cndmask_b32_e64 v49, v11, v28, s[36:37]
	v_cndmask_b32_e64 v46, v12, v29, s[38:39]
	v_add_f32_e32 v5, v3, v4
	v_sub_f32_e32 v4, v70, v48
	v_exp_f32_e32 v4, v4
	v_cndmask_b32_e64 v45, v13, v30, s[40:41]
	v_cndmask_b32_e64 v44, v14, v31, s[42:43]
	v_sub_f32_e32 v55, v55, v48
	v_add_f32_e32 v6, v4, v5
	v_sub_f32_e32 v5, v71, v48
	v_exp_f32_e32 v5, v5
	v_sub_f32_e32 v54, v54, v48
	v_sub_f32_e32 v52, v52, v48
	v_sub_f32_e32 v53, v53, v48
	v_add_f32_e32 v7, v5, v6
	v_sub_f32_e32 v6, v72, v48
	v_exp_f32_e32 v6, v6
	v_sub_f32_e32 v51, v51, v48
	v_sub_f32_e32 v50, v50, v48
	v_sub_f32_e32 v49, v49, v48
	v_add_f32_e32 v8, v6, v7
	v_sub_f32_e32 v7, v73, v48
	v_exp_f32_e32 v7, v7
	v_sub_f32_e32 v46, v46, v48
	v_sub_f32_e32 v45, v45, v48
	v_sub_f32_e32 v44, v44, v48
	v_add_f32_e32 v9, v7, v8
	v_sub_f32_e32 v8, v74, v48
	v_exp_f32_e32 v8, v8
	s_cmp_gt_i32 s93, 7
	v_add_f32_e32 v10, v8, v9
	v_sub_f32_e32 v9, v75, v48
	v_exp_f32_e32 v9, v9
	s_nop 0
	v_add_f32_e32 v11, v9, v10
	v_sub_f32_e32 v10, v58, v48
	v_exp_f32_e32 v10, v10
	s_nop 0
	v_add_f32_e32 v12, v10, v11
	v_sub_f32_e32 v11, v59, v48
	v_exp_f32_e32 v11, v11
	s_nop 0
	v_add_f32_e32 v13, v11, v12
	v_sub_f32_e32 v12, v60, v48
	v_exp_f32_e32 v12, v12
	v_exp_f32_e32 v60, v55
	v_add_f32_e32 v14, v12, v13
	v_sub_f32_e32 v13, v61, v48
	v_exp_f32_e32 v13, v13
	v_exp_f32_e32 v61, v54
	v_add_f32_e32 v15, v13, v14
	v_sub_f32_e32 v14, v62, v48
	v_exp_f32_e32 v14, v14
	v_exp_f32_e32 v62, v52
	v_add_f32_e32 v16, v14, v15
	v_sub_f32_e32 v15, v63, v48
	v_exp_f32_e32 v15, v15
	s_nop 0
	v_add_f32_e32 v17, v15, v16
	v_sub_f32_e32 v16, v32, v48
	v_exp_f32_e32 v16, v16
	s_nop 0
	v_add_f32_e32 v18, v16, v17
	v_sub_f32_e32 v17, v33, v48
	v_exp_f32_e32 v17, v17
	s_nop 0
	v_add_f32_e32 v19, v17, v18
	v_sub_f32_e32 v18, v34, v48
	v_exp_f32_e32 v18, v18
	s_nop 0
	v_add_f32_e32 v20, v18, v19
	v_sub_f32_e32 v19, v35, v48
	v_exp_f32_e32 v19, v19
	s_nop 0
	v_add_f32_e32 v21, v19, v20
	v_sub_f32_e32 v20, v36, v48
	v_exp_f32_e32 v20, v20
	s_nop 0
	v_add_f32_e32 v22, v20, v21
	v_sub_f32_e32 v21, v37, v48
	v_exp_f32_e32 v21, v21
	s_nop 0
	v_add_f32_e32 v23, v21, v22
	v_sub_f32_e32 v22, v38, v48
	v_exp_f32_e32 v22, v22
	s_nop 0
	v_add_f32_e32 v24, v22, v23
	v_sub_f32_e32 v23, v39, v48
	v_exp_f32_e32 v23, v23
	s_nop 0
	v_add_f32_e32 v25, v23, v24
	v_sub_f32_e32 v24, v40, v48
	v_exp_f32_e32 v24, v24
	s_nop 0
	v_add_f32_e32 v26, v24, v25
	v_sub_f32_e32 v25, v41, v48
	v_exp_f32_e32 v25, v25
	s_nop 0
	v_add_f32_e32 v27, v25, v26
	v_sub_f32_e32 v26, v42, v48
	v_exp_f32_e32 v26, v26
	s_nop 0
	v_add_f32_e32 v28, v26, v27
	v_sub_f32_e32 v27, v43, v48
	v_exp_f32_e32 v27, v27
	s_nop 0
	v_add_f32_e32 v29, v27, v28
	v_sub_f32_e32 v28, v78, v48
	v_exp_f32_e32 v28, v28
	s_nop 0
	v_add_f32_e32 v30, v28, v29
	v_sub_f32_e32 v29, v79, v48
	v_exp_f32_e32 v29, v29
	s_nop 0
	v_add_f32_e32 v31, v29, v30
	v_sub_f32_e32 v30, v97, v48
	v_exp_f32_e32 v30, v30
	s_nop 0
	v_add_f32_e32 v32, v30, v31
	v_sub_f32_e32 v31, v67, v48
	v_exp_f32_e32 v31, v31
	s_nop 0
	v_add_f32_e32 v33, v31, v32
	v_sub_f32_e32 v32, v107, v48
	v_exp_f32_e32 v32, v32
	v_exp_f32_e32 v107, v49
	v_add_f32_e32 v34, v32, v33
	v_sub_f32_e32 v33, v106, v48
	v_exp_f32_e32 v33, v33
	v_exp_f32_e32 v106, v50
	v_add_f32_e32 v35, v33, v34
	v_sub_f32_e32 v34, v105, v48
	v_exp_f32_e32 v34, v34
	v_exp_f32_e32 v105, v51
	v_add_f32_e32 v36, v34, v35
	v_sub_f32_e32 v35, v104, v48
	v_exp_f32_e32 v35, v35
	v_exp_f32_e32 v104, v53
	v_add_f32_e32 v37, v35, v36
	v_sub_f32_e32 v36, v103, v48
	v_exp_f32_e32 v36, v36
	s_nop 0
	v_add_f32_e32 v38, v36, v37
	v_sub_f32_e32 v37, v102, v48
	v_exp_f32_e32 v37, v37
	s_nop 0
	v_add_f32_e32 v39, v37, v38
	v_sub_f32_e32 v38, v101, v48
	v_exp_f32_e32 v38, v38
	s_nop 0
	v_add_f32_e32 v40, v38, v39
	v_sub_f32_e32 v39, v100, v48
	v_exp_f32_e32 v39, v39
	s_nop 0
	v_add_f32_e32 v41, v39, v40
	v_sub_f32_e32 v40, v99, v48
	v_exp_f32_e32 v40, v40
	s_nop 0
	v_add_f32_e32 v42, v40, v41
	v_sub_f32_e32 v41, v98, v48
	v_exp_f32_e32 v41, v41
	s_nop 0
	v_add_f32_e32 v43, v41, v42
	v_sub_f32_e32 v42, v76, v48
	v_exp_f32_e32 v42, v42
	s_nop 0
	v_add_f32_e32 v58, v42, v43
	v_sub_f32_e32 v43, v77, v48
	v_exp_f32_e32 v43, v43
	s_nop 0
	v_add_f32_e32 v58, v43, v58
	v_add_f32_e32 v55, v60, v58
	v_add_f32_e32 v54, v61, v55
	v_add_f32_e32 v52, v62, v54
	v_sub_f32_e32 v54, v57, v48
	v_exp_f32_e32 v63, v54
	v_sub_f32_e32 v54, v96, v48
	v_exp_f32_e32 v96, v54
	v_sub_f32_e32 v54, v112, v48
	v_exp_f32_e32 v97, v54
	v_sub_f32_e32 v54, v111, v48
	v_exp_f32_e32 v98, v54
	v_sub_f32_e32 v54, v110, v48
	v_add_f32_e32 v52, v63, v52
	v_exp_f32_e32 v99, v54
	v_sub_f32_e32 v54, v109, v48
	v_add_f32_e32 v52, v96, v52
	v_exp_f32_e32 v100, v54
	v_sub_f32_e32 v54, v108, v48
	v_add_f32_e32 v52, v97, v52
	v_exp_f32_e32 v101, v54
	v_sub_f32_e32 v54, v64, v48
	v_add_f32_e32 v52, v98, v52
	v_exp_f32_e32 v102, v54
	v_sub_f32_e32 v54, v56, v48
	v_add_f32_e32 v52, v99, v52
	v_exp_f32_e32 v103, v54
	v_add_f32_e32 v52, v100, v52
	v_add_f32_e32 v52, v101, v52
	v_add_f32_e32 v52, v102, v52
	v_add_f32_e32 v52, v103, v52
	v_add_f32_e32 v52, v104, v52
	v_exp_f32_e32 v108, v46
	v_add_f32_e32 v51, v105, v52
	v_exp_f32_e32 v109, v45
	v_add_f32_e32 v50, v106, v51
	v_add_f32_e32 v49, v107, v50
	v_add_f32_e32 v46, v108, v49
	v_add_f32_e32 v45, v109, v46
	v_exp_f32_e32 v46, v44
	s_nop 0
	v_add_f32_e32 v44, v46, v45
	v_sub_f32_e32 v45, v47, v48
	v_exp_f32_e32 v47, v45
	s_nop 0
	v_add_f32_e32 v44, v47, v44
	v_mov_b32_e32 v45, v44
	v_mov_b32_e32 v48, v44
	s_nop 1
	v_permlane32_swap_b32_e32 v45, v48
	v_cndmask_b32_e64 v45, v45, v48, s[6:7]
	v_add_f32_e32 v44, v44, v45
	v_max_f32_e32 v44, 0xda24260, v44
	v_div_scale_f32 v45, s[2:3], v44, v44, 1.0
	v_rcp_f32_e32 v48, v45
	s_nop 0
	v_fma_f32 v49, -v45, v48, 1.0
	v_fmac_f32_e32 v48, v49, v48
	v_div_scale_f32 v49, vcc, 1.0, v44, 1.0
	v_mul_f32_e32 v50, v49, v48
	v_fma_f32 v51, -v45, v50, v49
	v_fmac_f32_e32 v50, v51, v48
	v_fma_f32 v45, -v45, v50, v49
	v_div_fmas_f32 v45, v45, v48, v50
	v_div_fixup_f32 v110, v45, v44, 1.0
	v_pk_mul_f32 v[0:1], v[0:1], v[110:111] op_sel_hi:[1,0]
	v_pk_mul_f32 v[2:3], v[2:3], v[110:111] op_sel_hi:[1,0]
	v_pk_mul_f32 v[64:65], v[16:17], v[110:111] op_sel_hi:[1,0]
	v_add_f32_e32 v16, v2, v3
	v_add_f32_e32 v17, v0, v1
	v_pk_mul_f32 v[66:67], v[18:19], v[110:111] op_sel_hi:[1,0]
	v_add_f32_e32 v16, v17, v16
	v_mov_b32_e32 v17, v3
	v_mov_b32_e32 v18, v3
	s_nop 1
	v_permlane32_swap_b32_e32 v17, v18
	v_cndmask_b32_e64 v17, v17, v18, s[6:7]
	v_pk_mul_f32 v[4:5], v[4:5], v[110:111] op_sel_hi:[1,0]
	v_pk_mul_f32 v[6:7], v[6:7], v[110:111] op_sel_hi:[1,0]
	v_cndmask_b32_e64 v18, v17, 0, s[8:9]
	v_add_f32_e32 v16, v18, v16
	v_add_f32_e32 v18, v6, v7
	v_add_f32_e32 v19, v4, v5
	v_pk_mul_f32 v[68:69], v[20:21], v[110:111] op_sel_hi:[1,0]
	v_add_f32_e32 v18, v19, v18
	v_mov_b32_e32 v19, v7
	v_mov_b32_e32 v20, v7
	s_nop 1
	v_permlane32_swap_b32_e32 v19, v20
	v_cndmask_b32_e64 v19, v19, v20, s[6:7]
	v_cndmask_b32_e64 v17, v19, v17, s[8:9]
	v_pk_mul_f32 v[8:9], v[8:9], v[110:111] op_sel_hi:[1,0]
	v_pk_mul_f32 v[10:11], v[10:11], v[110:111] op_sel_hi:[1,0]
	v_pk_mul_f32 v[48:49], v[32:33], v[110:111] op_sel_hi:[1,0]
	v_pk_mul_f32 v[32:33], v[96:97], v[110:111] op_sel_hi:[1,0]
	v_add_f32_e32 v17, v17, v18
	v_add_u32_e32 v96, 0xa800, v194
	ds_write2_b32 v96, v16, v17 offset1:2
	v_add_f32_e32 v16, v10, v11
	v_add_f32_e32 v17, v8, v9
	v_add_f32_e32 v16, v17, v16
	v_mov_b32_e32 v17, v11
	v_mov_b32_e32 v18, v11
	s_nop 1
	v_permlane32_swap_b32_e32 v17, v18
	v_cndmask_b32_e64 v17, v17, v18, s[6:7]
	v_pk_mul_f32 v[12:13], v[12:13], v[110:111] op_sel_hi:[1,0]
	v_pk_mul_f32 v[14:15], v[14:15], v[110:111] op_sel_hi:[1,0]
	v_cndmask_b32_e64 v18, v17, v19, s[8:9]
	v_add_f32_e32 v16, v18, v16
	v_add_f32_e32 v18, v14, v15
	v_add_f32_e32 v19, v12, v13
	v_add_f32_e32 v18, v19, v18
	v_mov_b32_e32 v19, v15
	v_mov_b32_e32 v20, v15
	s_nop 1
	v_permlane32_swap_b32_e32 v19, v20
	v_cndmask_b32_e64 v97, v19, v20, s[6:7]
	v_cndmask_b32_e64 v17, v97, v17, s[8:9]
	v_add_f32_e32 v17, v17, v18
	ds_write2_b32 v96, v16, v17 offset0:4 offset1:6
	v_pk_mul_f32 v[70:71], v[22:23], v[110:111] op_sel_hi:[1,0]
	v_cvt_pk_bf16_f32 v16, v0, v1
	v_cvt_pk_bf16_f32 v17, v2, v3
	ds_read_b64_tr_b16 v[0:1], v160 offset:18432
	ds_read_b64_tr_b16 v[2:3], v160 offset:19968
	ds_read_b64_tr_b16 v[20:21], v160 offset:21504
	ds_read_b64_tr_b16 v[22:23], v160 offset:23040
	v_cvt_pk_bf16_f32 v18, v4, v5
	v_cvt_pk_bf16_f32 v19, v6, v7
	v_pk_mul_f32 v[50:51], v[34:35], v[110:111] op_sel_hi:[1,0]
	v_pk_mul_f32 v[52:53], v[36:37], v[110:111] op_sel_hi:[1,0]
	v_pk_mul_f32 v[34:35], v[98:99], v[110:111] op_sel_hi:[1,0]
	v_pk_mul_f32 v[36:37], v[100:101], v[110:111] op_sel_hi:[1,0]
	v_cvt_pk_bf16_f32 v98, v8, v9
	v_cvt_pk_bf16_f32 v99, v10, v11
	v_cvt_pk_bf16_f32 v100, v12, v13
	v_cvt_pk_bf16_f32 v101, v14, v15
	s_waitcnt lgkmcnt(2)
	v_mfma_f32_32x32x16_bf16 v[0:15], v[0:3], v[16:19], 0
	v_mul_f32_e64 v54, v38, v110
	v_mul_f32_e64 v55, v39, v110
	v_mul_f32_e64 v56, v40, v110
	v_mul_f32_e64 v57, v41, v110
	v_mul_f32_e64 v38, v102, v110
	v_mul_f32_e64 v39, v103, v110
	v_pk_mul_f32 v[40:41], v[104:105], v[110:111] op_sel_hi:[1,0]
	v_pk_mul_f32 v[72:73], v[24:25], v[110:111] op_sel_hi:[1,0]
	v_pk_mul_f32 v[74:75], v[26:27], v[110:111] op_sel_hi:[1,0]
	v_pk_mul_f32 v[76:77], v[28:29], v[110:111] op_sel_hi:[1,0]
	s_waitcnt lgkmcnt(0)
	v_mfma_f32_32x32x16_bf16 v[0:15], v[20:23], v[98:101], v[0:15]
	ds_read_b64_tr_b16 v[20:21], v160 offset:18496
	ds_read_b64_tr_b16 v[22:23], v160 offset:20032
	ds_read_b64_tr_b16 v[102:103], v160 offset:21568
	ds_read_b64_tr_b16 v[104:105], v160 offset:23104
	v_mul_f32_e64 v78, v30, v110
	v_mul_f32_e64 v79, v31, v110
	v_pk_mul_f32 v[58:59], v[42:43], v[110:111] op_sel_hi:[1,0]
	v_pk_mul_f32 v[60:61], v[60:61], v[110:111] op_sel_hi:[1,0]
	v_pk_mul_f32 v[62:63], v[62:63], v[110:111] op_sel_hi:[1,0]
	v_pk_mul_f32 v[42:43], v[106:107], v[110:111] op_sel_hi:[1,0]
	v_pk_mul_f32 v[44:45], v[108:109], v[110:111] op_sel_hi:[1,0]
	s_waitcnt lgkmcnt(2)
	v_mfma_f32_32x32x16_bf16 v[16:31], v[20:23], v[16:19], 0
	v_mul_f32_e64 v46, v46, v110
	v_mul_f32_e64 v47, v47, v110
	s_waitcnt lgkmcnt(0)
	v_mfma_f32_32x32x16_bf16 v[16:31], v[102:105], v[98:101], v[16:31]
	v_add_f32_e32 v98, v66, v67
	v_add_f32_e32 v99, v64, v65
	v_add_f32_e32 v98, v99, v98
	v_mov_b32_e32 v99, v67
	v_mov_b32_e32 v100, v67
	s_nop 1
	v_permlane32_swap_b32_e32 v99, v100
	v_cndmask_b32_e64 v99, v99, v100, s[6:7]
	v_cndmask_b32_e64 v97, v99, v97, s[8:9]
	v_add_f32_e32 v97, v97, v98
	v_add_f32_e32 v98, v70, v71
	v_add_f32_e32 v100, v68, v69
	v_add_f32_e32 v98, v100, v98
	v_mov_b32_e32 v100, v71
	v_mov_b32_e32 v101, v71
	s_nop 1
	v_permlane32_swap_b32_e32 v100, v101
	v_cndmask_b32_e64 v100, v100, v101, s[6:7]
	v_cndmask_b32_e64 v99, v100, v99, s[8:9]
	v_add_f32_e32 v98, v99, v98
	ds_write2_b32 v96, v97, v98 offset0:8 offset1:10
	v_add_f32_e32 v97, v74, v75
	v_add_f32_e32 v98, v72, v73
	v_add_f32_e32 v97, v98, v97
	v_mov_b32_e32 v98, v75
	v_mov_b32_e32 v99, v75
	s_nop 1
	v_permlane32_swap_b32_e32 v98, v99
	v_cndmask_b32_e64 v98, v98, v99, s[6:7]
	v_cndmask_b32_e64 v99, v98, v100, s[8:9]
	v_add_f32_e32 v97, v99, v97
	v_add_f32_e32 v99, v78, v79
	v_add_f32_e32 v100, v76, v77
	v_add_f32_e32 v99, v100, v99
	v_mov_b32_e32 v100, v79
	v_mov_b32_e32 v101, v79
	s_nop 1
	v_permlane32_swap_b32_e32 v100, v101
	v_cndmask_b32_e64 v100, v100, v101, s[6:7]
	v_cndmask_b32_e64 v98, v100, v98, s[8:9]
	v_add_f32_e32 v98, v98, v99
	ds_write2_b32 v96, v97, v98 offset0:12 offset1:14
	v_cvt_pk_bf16_f32 v64, v64, v65
	v_cvt_pk_bf16_f32 v65, v66, v67
	v_cvt_pk_bf16_f32 v66, v68, v69
	v_cvt_pk_bf16_f32 v67, v70, v71
	v_cvt_pk_bf16_f32 v68, v72, v73
	v_cvt_pk_bf16_f32 v69, v74, v75
	v_cvt_pk_bf16_f32 v70, v76, v77
	v_cvt_pk_bf16_f32 v71, v78, v79
	ds_read_b64_tr_b16 v[72:73], v160 offset:24576
	ds_read_b64_tr_b16 v[74:75], v160 offset:26112
	ds_read_b64_tr_b16 v[76:77], v160 offset:27648
	ds_read_b64_tr_b16 v[78:79], v160 offset:29184
	s_waitcnt lgkmcnt(2)
	v_mfma_f32_32x32x16_bf16 v[0:15], v[72:75], v[64:67], v[0:15]
	s_waitcnt lgkmcnt(0)
	v_mfma_f32_32x32x16_bf16 v[0:15], v[76:79], v[68:71], v[0:15]
	ds_read_b64_tr_b16 v[72:73], v160 offset:24640
	ds_read_b64_tr_b16 v[74:75], v160 offset:26176
	ds_read_b64_tr_b16 v[76:77], v160 offset:27712
	ds_read_b64_tr_b16 v[78:79], v160 offset:29248
	s_waitcnt lgkmcnt(2)
	v_mfma_f32_32x32x16_bf16 v[16:31], v[72:75], v[64:67], v[16:31]
	v_add_f32_e32 v64, v50, v51
	v_add_f32_e32 v65, v48, v49
	v_add_f32_e32 v64, v65, v64
	v_mov_b32_e32 v65, v51
	v_mov_b32_e32 v66, v51
	s_nop 1
	v_permlane32_swap_b32_e32 v65, v66
	v_cndmask_b32_e64 v65, v65, v66, s[6:7]
	v_cndmask_b32_e64 v66, v65, v100, s[8:9]
	v_add_f32_e32 v64, v66, v64
	v_add_f32_e32 v66, v54, v55
	v_add_f32_e32 v67, v52, v53
	s_waitcnt lgkmcnt(0)
	v_mfma_f32_32x32x16_bf16 v[16:31], v[76:79], v[68:71], v[16:31]
	v_add_f32_e32 v66, v67, v66
	v_mov_b32_e32 v67, v55
	v_mov_b32_e32 v68, v55
	s_nop 1
	v_permlane32_swap_b32_e32 v67, v68
	v_cndmask_b32_e64 v67, v67, v68, s[6:7]
	v_cndmask_b32_e64 v65, v67, v65, s[8:9]
	v_add_f32_e32 v65, v65, v66
	ds_write2_b32 v96, v64, v65 offset0:16 offset1:18
	v_add_f32_e32 v64, v58, v59
	v_add_f32_e32 v65, v56, v57
	v_add_f32_e32 v64, v65, v64
	v_mov_b32_e32 v65, v59
	v_mov_b32_e32 v66, v59
	s_nop 1
	v_permlane32_swap_b32_e32 v65, v66
	v_cndmask_b32_e64 v65, v65, v66, s[6:7]
	v_cndmask_b32_e64 v66, v65, v67, s[8:9]
	v_add_f32_e32 v64, v66, v64
	v_add_f32_e32 v66, v62, v63
	v_add_f32_e32 v67, v60, v61
	v_add_f32_e32 v66, v67, v66
	v_mov_b32_e32 v67, v63
	v_mov_b32_e32 v68, v63
	s_nop 1
	v_permlane32_swap_b32_e32 v67, v68
	v_cndmask_b32_e64 v67, v67, v68, s[6:7]
	v_cndmask_b32_e64 v65, v67, v65, s[8:9]
	v_add_f32_e32 v65, v65, v66
	ds_write2_b32 v96, v64, v65 offset0:20 offset1:22
	v_cvt_pk_bf16_f32 v48, v48, v49
	v_cvt_pk_bf16_f32 v49, v50, v51
	v_cvt_pk_bf16_f32 v50, v52, v53
	v_cvt_pk_bf16_f32 v51, v54, v55
	v_cvt_pk_bf16_f32 v52, v56, v57
	v_cvt_pk_bf16_f32 v53, v58, v59
	v_cvt_pk_bf16_f32 v54, v60, v61
	v_cvt_pk_bf16_f32 v55, v62, v63
	ds_read_b64_tr_b16 v[56:57], v160 offset:30720
	ds_read_b64_tr_b16 v[58:59], v160 offset:32256
	ds_read_b64_tr_b16 v[60:61], v160 offset:33792
	ds_read_b64_tr_b16 v[62:63], v160 offset:35328
	s_waitcnt lgkmcnt(2)
	v_mfma_f32_32x32x16_bf16 v[0:15], v[56:59], v[48:51], v[0:15]
	s_waitcnt lgkmcnt(0)
	v_mfma_f32_32x32x16_bf16 v[0:15], v[60:63], v[52:55], v[0:15]
	ds_read_b64_tr_b16 v[56:57], v160 offset:30784
	ds_read_b64_tr_b16 v[58:59], v160 offset:32320
	ds_read_b64_tr_b16 v[60:61], v160 offset:33856
	ds_read_b64_tr_b16 v[62:63], v160 offset:35392
	s_waitcnt lgkmcnt(2)
	v_mfma_f32_32x32x16_bf16 v[16:31], v[56:59], v[48:51], v[16:31]
	v_add_f32_e32 v48, v34, v35
	v_add_f32_e32 v49, v32, v33
	v_add_f32_e32 v48, v49, v48
	v_mov_b32_e32 v49, v35
	v_mov_b32_e32 v50, v35
	s_nop 1
	v_permlane32_swap_b32_e32 v49, v50
	v_cndmask_b32_e64 v49, v49, v50, s[6:7]
	v_cndmask_b32_e64 v50, v49, v67, s[8:9]
	v_add_f32_e32 v48, v50, v48
	v_add_f32_e32 v50, v38, v39
	v_add_f32_e32 v51, v36, v37
	s_waitcnt lgkmcnt(0)
	v_mfma_f32_32x32x16_bf16 v[16:31], v[60:63], v[52:55], v[16:31]
	v_add_f32_e32 v50, v51, v50
	v_mov_b32_e32 v51, v39
	v_mov_b32_e32 v52, v39
	s_nop 1
	v_permlane32_swap_b32_e32 v51, v52
	v_cndmask_b32_e64 v51, v51, v52, s[6:7]
	v_cndmask_b32_e64 v49, v51, v49, s[8:9]
	v_add_f32_e32 v49, v49, v50
	ds_write2_b32 v96, v48, v49 offset0:24 offset1:26
	v_add_f32_e32 v48, v42, v43
	v_add_f32_e32 v49, v40, v41
	v_add_f32_e32 v48, v49, v48
	v_mov_b32_e32 v49, v43
	v_mov_b32_e32 v50, v43
	s_nop 1
	v_permlane32_swap_b32_e32 v49, v50
	v_cndmask_b32_e64 v49, v49, v50, s[6:7]
	v_cndmask_b32_e64 v50, v49, v51, s[8:9]
	v_add_f32_e32 v48, v50, v48
	v_add_f32_e32 v50, v46, v47
	v_add_f32_e32 v51, v44, v45
	v_add_f32_e32 v50, v51, v50
	v_mov_b32_e32 v51, v47
	v_mov_b32_e32 v52, v47
	s_nop 1
	v_permlane32_swap_b32_e32 v51, v52
	v_cndmask_b32_e64 v51, v51, v52, s[6:7]
	v_cndmask_b32_e64 v49, v51, v49, s[8:9]
	v_add_f32_e32 v49, v49, v50
	ds_write2_b32 v96, v48, v49 offset0:28 offset1:30
	v_cvt_pk_bf16_f32 v32, v32, v33
	v_cvt_pk_bf16_f32 v33, v34, v35
	v_cvt_pk_bf16_f32 v34, v36, v37
	v_cvt_pk_bf16_f32 v35, v38, v39
	v_cvt_pk_bf16_f32 v36, v40, v41
	v_cvt_pk_bf16_f32 v37, v42, v43
	v_cvt_pk_bf16_f32 v38, v44, v45
	v_cvt_pk_bf16_f32 v39, v46, v47
	ds_read_b64_tr_b16 v[40:41], v160 offset:36864
	ds_read_b64_tr_b16 v[42:43], v160 offset:38400
	ds_read_b64_tr_b16 v[44:45], v160 offset:39936
	ds_read_b64_tr_b16 v[46:47], v160 offset:41472
	s_waitcnt lgkmcnt(2)
	v_mfma_f32_32x32x16_bf16 v[0:15], v[40:43], v[32:35], v[0:15]
	s_waitcnt lgkmcnt(0)
	v_mfma_f32_32x32x16_bf16 v[0:15], v[44:47], v[36:39], v[0:15]
	ds_read_b64_tr_b16 v[40:41], v160 offset:36928
	ds_read_b64_tr_b16 v[42:43], v160 offset:38464
	ds_read_b64_tr_b16 v[44:45], v160 offset:40000
	ds_read_b64_tr_b16 v[46:47], v160 offset:41536
	s_waitcnt lgkmcnt(2)
	v_mfma_f32_32x32x16_bf16 v[16:31], v[40:43], v[32:35], v[16:31]
	s_nop 5
	v_mul_f32_e32 v0, v128, v0
	v_mul_f32_e32 v1, v128, v1
	ds_write2st64_b32 v195, v0, v1 offset1:8
	v_mul_f32_e32 v0, v128, v2
	v_mul_f32_e32 v1, v128, v3
	ds_write2st64_b32 v195, v0, v1 offset0:16 offset1:24
	v_mul_f32_e32 v0, v128, v4
	s_waitcnt lgkmcnt(2)
	v_mfma_f32_32x32x16_bf16 v[16:31], v[44:47], v[36:39], v[16:31]
	v_mul_f32_e32 v1, v128, v5
	ds_write2st64_b32 v195, v0, v1 offset0:32 offset1:40
	v_mul_f32_e32 v0, v128, v6
	v_mul_f32_e32 v1, v128, v7
	ds_write2st64_b32 v195, v0, v1 offset0:48 offset1:56
	v_mul_f32_e32 v0, v128, v8
	v_mul_f32_e32 v1, v128, v9
	ds_write2st64_b32 v195, v0, v1 offset0:64 offset1:72
	v_mul_f32_e32 v0, v128, v10
	v_mul_f32_e32 v1, v128, v11
	ds_write2st64_b32 v195, v0, v1 offset0:80 offset1:88
	v_mul_f32_e32 v0, v128, v12
	v_mul_f32_e32 v1, v128, v13
	ds_write2st64_b32 v195, v0, v1 offset0:96 offset1:104
	v_mul_f32_e32 v0, v128, v14
	v_mul_f32_e32 v1, v128, v15
	ds_write2st64_b32 v195, v0, v1 offset0:112 offset1:120
	v_mul_f32_e32 v0, v128, v16
	v_mul_f32_e32 v1, v128, v17
	ds_write2st64_b32 v195, v0, v1 offset0:128 offset1:136
	v_mul_f32_e32 v0, v128, v18
	v_mul_f32_e32 v1, v128, v19
	ds_write2st64_b32 v195, v0, v1 offset0:144 offset1:152
	v_mul_f32_e32 v0, v128, v20
	v_mul_f32_e32 v1, v128, v21
	ds_write2st64_b32 v195, v0, v1 offset0:160 offset1:168
	v_mul_f32_e32 v0, v128, v22
	v_mul_f32_e32 v1, v128, v23
	ds_write2st64_b32 v195, v0, v1 offset0:176 offset1:184
	v_mul_f32_e32 v0, v128, v24
	v_mul_f32_e32 v1, v128, v25
	ds_write2st64_b32 v195, v0, v1 offset0:192 offset1:200
	v_mul_f32_e32 v0, v128, v26
	v_mul_f32_e32 v1, v128, v27
	ds_write2st64_b32 v195, v0, v1 offset0:208 offset1:216
	v_mul_f32_e32 v0, v128, v28
	v_mul_f32_e32 v1, v128, v29
	ds_write2st64_b32 v195, v0, v1 offset0:224 offset1:232
	v_mul_f32_e32 v0, v128, v30
	v_mul_f32_e32 v1, v128, v31
	ds_write2st64_b32 v195, v0, v1 offset0:240 offset1:248
	s_waitcnt lgkmcnt(0)
	s_barrier
	s_cbranch_scc0 .LBB0_1004
	s_add_i32 s2, s93, -2
	v_mov_b32_e32 v4, -1.0
	s_mov_b64 s[4:5], exec
	v_readlane_b32 s12, v240, 45
	v_readlane_b32 s13, v240, 46
	s_and_b64 s[12:13], s[4:5], s[12:13]
	s_mov_b64 exec, s[12:13]
	s_cbranch_execz .LBB0_943
	ds_read2st64_b32 v[0:1], v197 offset0:168 offset1:201
	ds_read_b32 v2, v197 offset:59904
	ds_read_b32 v3, v198 offset:25344
	v_cmp_ge_u32_e32 vcc, s2, v196
	s_waitcnt lgkmcnt(2)
	v_add_f32_e32 v0, v0, v1
	s_waitcnt lgkmcnt(1)
	v_add_f32_e32 v0, v0, v2
	s_waitcnt lgkmcnt(0)
	v_add_f32_e32 v0, v0, v3
	v_cndmask_b32_e32 v4, -1.0, v0, vcc

.LBB0_1006:
	s_mov_b64 s[4:5], exec
	v_readlane_b32 s2, v240, 43
	v_readlane_b32 s3, v240, 44
	s_and_b64 s[2:3], s[4:5], s[2:3]
	s_mov_b64 exec, s[2:3]
	ds_write_b32 v202, v0
	s_or_b64 exec, exec, s[4:5]
	s_lshl_b64 s[50:51], s[0:1], 18
	v_readlane_b32 s1, v240, 47
	s_add_u32 s2, s1, s50
	v_readlane_b32 s1, v240, 48
	s_addc_u32 s3, s1, s51
	v_readlane_b32 s1, v240, 49
	s_add_u32 s4, s1, s50
	v_readlane_b32 s1, v240, 50
	s_addc_u32 s5, s1, s51
	v_lshl_add_u64 v[0:1], s[4:5], 0, v[152:153]
	s_waitcnt lgkmcnt(0)
	s_barrier
	v_lshl_add_u64 v[2:3], s[2:3], 0, v[152:153]
	s_waitcnt vmcnt(0)
	v_mov_b64_e32 v[100:101], v[220:221]
	v_mov_b64_e32 v[102:103], v[222:223]
	v_mov_b64_e32 v[96:97], v[216:217]
	v_mov_b64_e32 v[98:99], v[218:219]
	ds_read_b32 v128, v203
	s_cmp_lt_i32 s93, 1
	s_cbranch_scc1 .LBB0_1010
	v_add_co_u32_e32 v2, vcc, 0x2000, v2
	s_nop 1
	v_addc_co_u32_e32 v3, vcc, 0, v3, vcc
	v_add_co_u32_e32 v0, vcc, 0x2000, v0
	s_nop 1
	v_addc_co_u32_e32 v1, vcc, 0, v1, vcc
	v_mov_b64_e32 v[104:105], v[224:225]
	v_mov_b64_e32 v[106:107], v[226:227]
	v_mov_b64_e32 v[108:109], v[228:229]
	v_mov_b64_e32 v[110:111], v[230:231]
